# v143 + first phase boundary uses the kernel's own grid barrier instead of cooperative-groups grid.sync
# baseline (speedup 1.0000x reference)
.LBB0_92:
	v_readlane_b32 s0, v255, 25
	s_cmp_eq_u32 s0, 0
	s_cselect_b64 s[2:3], -1, 0
	v_readlane_b32 s1, v255, 26
	v_writelane_b32 v255, s2, 27
	s_cmp_lg_u32 s0, 0
	s_mov_b64 s[0:1], -1
	v_writelane_b32 v255, s3, 28
	v_readlane_b32 s2, v253, 1
	v_readlane_b32 s3, v253, 2
	s_waitcnt vmcnt(0)
	s_barrier
	s_mov_b64 s[0:1], exec
	v_readlane_b32 s4, v253, 5
	v_readlane_b32 s5, v253, 6
	s_and_b64 s[4:5], s[0:1], s[4:5]
	s_mov_b64 exec, s[4:5]
	s_cbranch_execz .LBB0_145
	s_load_dwordx2 s[4:5], s[2:3], 0xd8
	v_readlane_b32 s2, v255, 17
	s_waitcnt vmcnt(0) expcnt(0) lgkmcnt(0)
	s_nop 0
	v_mov_b32_e32 v0, s2
	ds_read_b32 v3, v0
	v_readlane_b32 s2, v255, 18
	s_waitcnt lgkmcnt(0)
	v_cmp_ne_u32_e32 vcc, 0, v3
	v_mov_b32_e32 v0, s2
	ds_read_b32 v2, v0
	s_cbranch_vccnz .LBB0_109
	s_add_u32 s6, s4, 0x1000
	s_addc_u32 s7, s5, 0
	s_add_u32 s8, s4, 0x1100
	s_addc_u32 s9, s5, 0
	s_add_u32 s10, s4, 0x1200
	s_addc_u32 s11, s5, 0
	s_add_u32 s14, s4, 0x1300
	s_addc_u32 s15, s5, 0
	s_mov_b32 s20, 1
	s_branch .LBB0_97
